# attention phase with 6 of 8 waves pulling tasks (was 4)
# baseline (speedup 1.0000x reference)
; __device__ __forceinline__ void attn_phase(const Ctx& c, ArgsP a, int l, int ctr_slot) {
;     unsigned* ctr0 = (unsigned*)(c.ws + WS_CTL) + 64 * ctr_slot;
;     const int myq = (int)(__builtin_amdgcn_s_getreg((3 << 11) | 20) & 7u);
;     for (int qi = 0; qi < 8; ++qi) {
;         const int q = (myq + qi) & 7;
;         unsigned* ctr = ctr0 + 64 * q;
;         for (;;) {
;             int t = 0;
;             if (c.lane == 0) t = (int)atomicAdd(ctr, 1u);
;             t = __builtin_amdgcn_readfirstlane(t);
;             if (t >= 448) break;
;             Ctx ct = c; { int ln = c.lane; asm volatile("" : "+v"(ln)); ct.lane = ln; }
;             int ll = l; asm volatile("" : "+s"(ll));
.LBB0_119:
	s_and_b64 vcc, exec, s[4:5]
	s_cbranch_vccz .LBB0_332
	s_cmp_gt_i32 s2, 2
	s_mov_b64 s[4:5], -1
	s_cbranch_scc0 .LBB0_328
	s_add_u32 s3, s48, 0x25700000
	v_writelane_b32 v255, s3, 20
	s_addc_u32 s3, s49, 0
	v_writelane_b32 v255, s3, 21
	s_cmp_lt_i32 s2, 4
	s_cbranch_scc1 .LBB0_235
	s_cmp_gt_i32 s2, 4
	s_cbranch_scc0 .LBB0_220
	s_lshl_b32 s2, s67, 9
	s_ashr_i32 s3, s2, 31
	v_readlane_b32 s4, v254, 47
	s_add_u32 s2, s4, s2
	v_readlane_b32 s4, v254, 48
	s_addc_u32 s3, s4, s3
	s_lshl_b64 s[2:3], s[2:3], 2
	v_writelane_b32 v255, s67, 22
	s_add_u32 s2, s48, s2
	v_writelane_b32 v255, s2, 30
	s_addc_u32 s2, s49, s3
	v_writelane_b32 v255, s2, 31
	s_getreg_b32 s2, hwreg(HW_REG_XCC_ID, 0, 4)
	v_writelane_b32 v255, s2, 32
	s_add_u32 s2, s48, 0x2b400000
	v_writelane_b32 v255, s2, 26
	s_addc_u32 s2, s49, 0
	v_writelane_b32 v255, s2, 28
	s_add_u32 s2, s48, 0x2e900000
	v_writelane_b32 v255, s2, 23
	s_addc_u32 s2, s49, 0
	v_writelane_b32 v255, s2, 24
	v_readlane_b32 s2, v254, 62
	s_lshl_b32 s2, s2, 14
	s_add_i32 s52, s2, 0
	s_add_u32 s77, s48, 0x2dd00000
	s_addc_u32 s2, s49, 0
	s_add_u32 s3, s48, 0x2a700000
	s_addc_u32 s63, s49, 0
	s_add_u32 s88, s48, 0x2d500000
	s_addc_u32 s89, s49, 0
	s_add_u32 s51, s48, 0x2b500000
	s_mov_b32 s67, 0
	v_cmp_eq_u32_e64 s[6:7], 0, v198
	v_writelane_b32 v255, s2, 25
	s_addc_u32 s95, s49, 0
	v_readlane_b32 s4, v254, 62
	s_nop 3
	s_cmp_gt_u32 s4, 5
	s_cbranch_scc1 .LBB0_219
	s_branch .LBB0_125
